# prompt attention tile step hand-scheduled: batched K/V fragment LDS reads, permlane max (plus counted vmcnt, Fdn1 tail move)
# speedup vs baseline: 1.0059x; 1.0059x over previous
.Lpa0_tile:
	v_or_b32_e32 v66, s33, v149
	v_mad_u32_u24 v188, v66, s97, v176
	ds_read_b128 v[206:209], v188
	ds_read_b128 v[210:213], v188 offset:32
	ds_read_b128 v[214:217], v188 offset:64
	ds_read_b128 v[224:227], v188 offset:96
	ds_read_b128 v[232:235], v188 offset:128
	ds_read_b128 v[236:239], v188 offset:160
	ds_read_b128 v[240:243], v188 offset:192
	ds_read_b128 v[184:187], v188 offset:224
	v_add_u32_e32 v190, s33, v183
	v_lshl_add_u32 v197, s33, 1, v180
	v_cmp_gt_i32_e64 s[12:13], s61, v190
	v_cmp_lt_i32_e64 s[0:1], s64, v190
	v_add_u32_e32 v198, 0x4400, v197
	v_add_u32_e32 v201, 0x5600, v197
	v_add_u32_e32 v203, 0x6800, v197
	v_add_u32_e32 v197, 0x7a00, v197
	s_waitcnt lgkmcnt(7)
	v_mfma_f32_32x32x16_bf16 v[66:81], v[206:209], v[102:105], 0
	s_waitcnt lgkmcnt(6)
	v_mfma_f32_32x32x16_bf16 v[66:81], v[210:213], v[106:109], v[66:81]
	s_waitcnt lgkmcnt(5)
	v_mfma_f32_32x32x16_bf16 v[66:81], v[214:217], v[114:117], v[66:81]
	s_waitcnt lgkmcnt(4)
	v_mfma_f32_32x32x16_bf16 v[66:81], v[224:227], v[118:121], v[66:81]
	s_waitcnt lgkmcnt(3)
	v_mfma_f32_32x32x16_bf16 v[66:81], v[232:235], v[122:125], v[66:81]
	s_waitcnt lgkmcnt(2)
	v_mfma_f32_32x32x16_bf16 v[66:81], v[236:239], v[126:129], v[66:81]
	s_waitcnt lgkmcnt(1)
	v_mfma_f32_32x32x16_bf16 v[66:81], v[240:243], v[130:133], v[66:81]
	s_waitcnt lgkmcnt(0)
	v_mfma_f32_32x32x16_bf16 v[66:81], v[184:187], v[134:137], v[66:81]
	s_and_saveexec_b64 s[14:15], s[0:1]
	s_cbranch_execz .Lpa0_nobias
	v_add_u32_e32 v190, v190, v148
	v_med3_i32 v188, v190, s39, 63
	v_lshl_add_u32 v188, v188, 2, s66
	v_add_u32_e32 v192, 1, v190
	v_med3_i32 v192, v192, s39, 63
	v_lshl_add_u32 v192, v192, 2, s66
	v_add_u32_e32 v193, 2, v190
	v_med3_i32 v193, v193, s39, 63
	v_lshl_add_u32 v193, v193, 2, s66
	v_add_u32_e32 v194, 3, v190
	v_med3_i32 v194, v194, s39, 63
	v_lshl_add_u32 v194, v194, 2, s66
	v_add_u32_e32 v195, 8, v190
	v_med3_i32 v195, v195, s39, 63
	v_lshl_add_u32 v195, v195, 2, s66
	v_add_u32_e32 v196, 9, v190
	v_med3_i32 v196, v196, s39, 63
	v_lshl_add_u32 v196, v196, 2, s66
	v_add_u32_e32 v199, 10, v190
	v_med3_i32 v199, v199, s39, 63
	v_lshl_add_u32 v199, v199, 2, s66
	v_add_u32_e32 v200, 11, v190
	v_med3_i32 v200, v200, s39, 63
	v_lshl_add_u32 v200, v200, 2, s66
	v_add_u32_e32 v202, 16, v190
	v_med3_i32 v202, v202, s39, 63
	v_lshl_add_u32 v202, v202, 2, s66
	v_add_u32_e32 v204, 17, v190
	v_med3_i32 v204, v204, s39, 63
	v_lshl_add_u32 v204, v204, 2, s66
	v_add_u32_e32 v205, 18, v190
	v_med3_i32 v205, v205, s39, 63
	v_lshl_add_u32 v205, v205, 2, s66
	v_add_u32_e32 v218, 19, v190
	v_med3_i32 v218, v218, s39, 63
	v_lshl_add_u32 v218, v218, 2, s66
	v_add_u32_e32 v219, 24, v190
	v_med3_i32 v219, v219, s39, 63
	v_lshl_add_u32 v219, v219, 2, s66
	v_add_u32_e32 v223, 25, v190
	v_med3_i32 v223, v223, s39, 63
	v_lshl_add_u32 v223, v223, 2, s66
	v_add_u32_e32 v244, 26, v190
	v_med3_i32 v244, v244, s39, 63
	v_lshl_add_u32 v244, v244, 2, s66
	v_add_u32_e32 v190, 27, v190
	v_med3_i32 v190, v190, s39, 63
	v_lshl_add_u32 v190, v190, 2, s66
	ds_read_b32 v188, v188 offset:512
	ds_read_b32 v192, v192 offset:512
	ds_read_b32 v193, v193 offset:512
	ds_read_b32 v194, v194 offset:512
	ds_read_b32 v195, v195 offset:512
	ds_read_b32 v196, v196 offset:512
	ds_read_b32 v199, v199 offset:512
	ds_read_b32 v200, v200 offset:512
	ds_read_b32 v202, v202 offset:512
	ds_read_b32 v204, v204 offset:512
	ds_read_b32 v205, v205 offset:512
	ds_read_b32 v218, v218 offset:512
	ds_read_b32 v219, v219 offset:512
	ds_read_b32 v223, v223 offset:512
	ds_read_b32 v244, v244 offset:512
	ds_read_b32 v190, v190 offset:512
	s_mov_b64 exec, s[14:15]
	ds_read2_b64 v[206:209], v198 offset1:2
	ds_read2_b64 v[210:213], v201 offset1:2
	ds_read2_b64 v[214:217], v203 offset1:2
	ds_read2_b64 v[224:227], v197 offset1:2
	ds_read2_b64 v[232:235], v198 offset0:4 offset1:6
	ds_read2_b64 v[236:239], v201 offset0:4 offset1:6
	ds_read2_b64 v[240:243], v203 offset0:4 offset1:6
	ds_read2_b64 v[184:187], v197 offset0:4 offset1:6
	s_waitcnt lgkmcnt(8)
	s_and_b64 exec, s[14:15], s[0:1]
	v_add_f32_e32 v66, v66, v188
	v_add_f32_e32 v67, v67, v192
	v_add_f32_e32 v68, v68, v193
	v_add_f32_e32 v69, v69, v194
	v_add_f32_e32 v70, v70, v195
	v_add_f32_e32 v71, v71, v196
	v_add_f32_e32 v72, v72, v199
	v_add_f32_e32 v73, v73, v200
	v_add_f32_e32 v74, v74, v202
	v_add_f32_e32 v75, v75, v204
	v_add_f32_e32 v76, v76, v205
	v_add_f32_e32 v77, v77, v218
	v_add_f32_e32 v78, v78, v219
	v_add_f32_e32 v79, v79, v223
	v_add_f32_e32 v80, v80, v244
	v_add_f32_e32 v81, v81, v190
	s_mov_b64 exec, s[14:15]
	s_branch .Lpa0_max
.Lpa0_nobias:
	s_mov_b64 exec, s[14:15]
	ds_read2_b64 v[206:209], v198 offset1:2
	ds_read2_b64 v[210:213], v201 offset1:2
	ds_read2_b64 v[214:217], v203 offset1:2
	ds_read2_b64 v[224:227], v197 offset1:2
	ds_read2_b64 v[232:235], v198 offset0:4 offset1:6
	ds_read2_b64 v[236:239], v201 offset0:4 offset1:6
	ds_read2_b64 v[240:243], v203 offset0:4 offset1:6
	ds_read2_b64 v[184:187], v197 offset0:4 offset1:6
	s_nop 1
.Lpa0_max:
	v_cndmask_b32_e64 v192, 0, v157, s[12:13]
	v_max3_f32 v193, v66, v67, v68
	v_max3_f32 v194, v69, v70, v71
	v_max3_f32 v195, v72, v73, v74
	v_max3_f32 v196, v75, v76, v77
	v_max3_f32 v199, v78, v79, v80
	v_max3_f32 v193, v193, v194, v195
	v_max3_f32 v196, v196, v199, v81
	v_max_f32_e32 v193, v193, v196
	v_add_f32_e32 v193, v192, v193
	v_mov_b32_e32 v194, v193
	s_nop 1
	v_permlane32_swap_b32_e32 v194, v193
	v_max_f32_e32 v193, v193, v194
	v_sub_f32_e32 v195, v193, v182
	v_cmp_lt_f32_e32 vcc, s60, v195
	s_cbranch_vccz .Lpa0_exp
	v_max_f32_e32 v193, v182, v193
	v_sub_f32_e32 v182, v182, v193
	v_exp_f32_e32 v182, v182
	s_nop 0
	v_mul_f32_e32 v153, v153, v182
	v_pk_mul_f32 v[64:65], v[64:65], v[182:183] op_sel_hi:[1,0]
	v_pk_mul_f32 v[62:63], v[62:63], v[182:183] op_sel_hi:[1,0]
	v_pk_mul_f32 v[60:61], v[60:61], v[182:183] op_sel_hi:[1,0]
	v_pk_mul_f32 v[58:59], v[58:59], v[182:183] op_sel_hi:[1,0]
	v_pk_mul_f32 v[56:57], v[56:57], v[182:183] op_sel_hi:[1,0]
	v_pk_mul_f32 v[54:55], v[54:55], v[182:183] op_sel_hi:[1,0]
	v_pk_mul_f32 v[52:53], v[52:53], v[182:183] op_sel_hi:[1,0]
	v_pk_mul_f32 v[50:51], v[50:51], v[182:183] op_sel_hi:[1,0]
	v_pk_mul_f32 v[48:49], v[48:49], v[182:183] op_sel_hi:[1,0]
	v_pk_mul_f32 v[46:47], v[46:47], v[182:183] op_sel_hi:[1,0]
	v_pk_mul_f32 v[44:45], v[44:45], v[182:183] op_sel_hi:[1,0]
	v_pk_mul_f32 v[42:43], v[42:43], v[182:183] op_sel_hi:[1,0]
	v_pk_mul_f32 v[40:41], v[40:41], v[182:183] op_sel_hi:[1,0]
	v_pk_mul_f32 v[38:39], v[38:39], v[182:183] op_sel_hi:[1,0]
	v_pk_mul_f32 v[36:37], v[36:37], v[182:183] op_sel_hi:[1,0]
	v_pk_mul_f32 v[34:35], v[34:35], v[182:183] op_sel_hi:[1,0]
	v_pk_mul_f32 v[32:33], v[32:33], v[182:183] op_sel_hi:[1,0]
	v_pk_mul_f32 v[30:31], v[30:31], v[182:183] op_sel_hi:[1,0]
	v_pk_mul_f32 v[28:29], v[28:29], v[182:183] op_sel_hi:[1,0]
	v_pk_mul_f32 v[26:27], v[26:27], v[182:183] op_sel_hi:[1,0]
	v_pk_mul_f32 v[24:25], v[24:25], v[182:183] op_sel_hi:[1,0]
	v_pk_mul_f32 v[22:23], v[22:23], v[182:183] op_sel_hi:[1,0]
	v_pk_mul_f32 v[20:21], v[20:21], v[182:183] op_sel_hi:[1,0]
	v_pk_mul_f32 v[18:19], v[18:19], v[182:183] op_sel_hi:[1,0]
	v_pk_mul_f32 v[16:17], v[16:17], v[182:183] op_sel_hi:[1,0]
	v_pk_mul_f32 v[14:15], v[14:15], v[182:183] op_sel_hi:[1,0]
	v_pk_mul_f32 v[12:13], v[12:13], v[182:183] op_sel_hi:[1,0]
	v_pk_mul_f32 v[10:11], v[10:11], v[182:183] op_sel_hi:[1,0]
	v_pk_mul_f32 v[8:9], v[8:9], v[182:183] op_sel_hi:[1,0]
	v_pk_mul_f32 v[6:7], v[6:7], v[182:183] op_sel_hi:[1,0]
	v_pk_mul_f32 v[4:5], v[4:5], v[182:183] op_sel_hi:[1,0]
	v_pk_mul_f32 v[2:3], v[2:3], v[182:183] op_sel_hi:[1,0]
	v_mov_b32_e32 v182, v193
.Lpa0_exp:
	v_sub_f32_e32 v188, v192, v182
	v_add_f32_e32 v66, v66, v188
	v_add_f32_e32 v67, v67, v188
	v_add_f32_e32 v68, v68, v188
	v_add_f32_e32 v69, v69, v188
	v_add_f32_e32 v70, v70, v188
	v_add_f32_e32 v71, v71, v188
	v_add_f32_e32 v72, v72, v188
	v_add_f32_e32 v73, v73, v188
	v_exp_f32_e32 v66, v66
	v_exp_f32_e32 v67, v67
	v_exp_f32_e32 v68, v68
	v_exp_f32_e32 v69, v69
	v_exp_f32_e32 v70, v70
	v_exp_f32_e32 v71, v71
	v_exp_f32_e32 v72, v72
	v_exp_f32_e32 v73, v73
	v_add_f32_e32 v200, v66, v67
	v_add_f32_e32 v202, v68, v69
	v_add_f32_e32 v204, v70, v71
	v_add_f32_e32 v205, v72, v73
	v_cvt_pk_bf16_f32 v192, v66, v67
	v_cvt_pk_bf16_f32 v193, v68, v69
	v_cvt_pk_bf16_f32 v194, v70, v71
	v_cvt_pk_bf16_f32 v195, v72, v73
	v_add_f32_e32 v200, v200, v202
	v_add_f32_e32 v204, v204, v205
	s_waitcnt lgkmcnt(4)
	v_mfma_f32_32x32x16_bf16 v[50:65], v[206:209], v[192:195], v[50:65]
	v_add_f32_e32 v74, v74, v188
	v_add_f32_e32 v75, v75, v188
	v_exp_f32_e32 v74, v74
	v_exp_f32_e32 v75, v75
	v_add_f32_e32 v76, v76, v188
	v_add_f32_e32 v77, v77, v188
	v_mfma_f32_32x32x16_bf16 v[34:49], v[210:213], v[192:195], v[34:49]
	v_exp_f32_e32 v76, v76
	v_exp_f32_e32 v77, v77
	v_add_f32_e32 v78, v78, v188
	v_add_f32_e32 v79, v79, v188
	v_exp_f32_e32 v78, v78
	v_exp_f32_e32 v79, v79
	v_mfma_f32_32x32x16_bf16 v[18:33], v[214:217], v[192:195], v[18:33]
	v_add_f32_e32 v80, v80, v188
	v_add_f32_e32 v81, v81, v188
	v_exp_f32_e32 v80, v80
	v_exp_f32_e32 v81, v81
	v_add_f32_e32 v200, v200, v204
	v_add_f32_e32 v202, v74, v75
	v_mfma_f32_32x32x16_bf16 v[2:17], v[224:227], v[192:195], v[2:17]
	v_add_f32_e32 v204, v76, v77
	v_add_f32_e32 v205, v78, v79
	v_add_f32_e32 v218, v80, v81
	v_cvt_pk_bf16_f32 v196, v74, v75
	v_cvt_pk_bf16_f32 v197, v76, v77
	v_cvt_pk_bf16_f32 v198, v78, v79
	v_cvt_pk_bf16_f32 v199, v80, v81
	v_add_f32_e32 v202, v202, v204
	v_add_f32_e32 v205, v205, v218
	s_waitcnt lgkmcnt(0)
	v_mfma_f32_32x32x16_bf16 v[50:65], v[232:235], v[196:199], v[50:65]
	v_add_f32_e32 v202, v202, v205
	v_mfma_f32_32x32x16_bf16 v[34:49], v[236:239], v[196:199], v[34:49]
	v_add_f32_e32 v200, v200, v202
	v_mfma_f32_32x32x16_bf16 v[18:33], v[240:243], v[196:199], v[18:33]
	v_add_f32_e32 v153, v153, v200
	v_mfma_f32_32x32x16_bf16 v[2:17], v[184:187], v[196:199], v[2:17]
	s_add_i32 s33, s33, 32
	s_cmp_lt_u32 s33, 64
	s_cbranch_scc1 .Lpa0_tile

.LBB0_90:
	s_or_b32 s0, s31, 1
	s_cmp_lt_i32 s0, s26
	s_cselect_b64 s[12:13], -1, 0
	s_cmp_ge_i32 s31, s22
	s_cselect_b64 s[14:15], -1, 0
	s_or_b64 s[12:13], s[14:15], s[12:13]
	s_and_b64 vcc, exec, s[12:13]
	s_cbranch_vccnz .LBB0_97
	s_lshl_b32 s0, s0, 6
	v_sub_u32_e32 v183, s0, v155
	s_mov_b32 s33, 0
.Lpa1_tile:
	v_or_b32_e32 v66, s33, v149
	v_mad_u32_u24 v188, v66, s97, v176
	ds_read_b128 v[206:209], v188 offset:35840
	ds_read_b128 v[210:213], v188 offset:35872
	ds_read_b128 v[214:217], v188 offset:35904
	ds_read_b128 v[224:227], v188 offset:35936
	ds_read_b128 v[232:235], v188 offset:35968
	ds_read_b128 v[236:239], v188 offset:36000
	ds_read_b128 v[240:243], v188 offset:36032
	ds_read_b128 v[184:187], v188 offset:36064
	v_add_u32_e32 v190, s33, v183
	v_lshl_add_u32 v197, s33, 1, v180
	v_cmp_gt_i32_e64 s[12:13], s61, v190
	v_cmp_lt_i32_e64 s[0:1], s64, v190
	v_add_u32_e32 v198, 0xd000, v197
	v_add_u32_e32 v201, 0xe200, v197
	v_add_u32_e32 v203, 0xf400, v197
	v_add_u32_e32 v197, 0x10600, v197
	s_waitcnt lgkmcnt(7)
	v_mfma_f32_32x32x16_bf16 v[66:81], v[206:209], v[102:105], 0
	s_waitcnt lgkmcnt(6)
	v_mfma_f32_32x32x16_bf16 v[66:81], v[210:213], v[106:109], v[66:81]
	s_waitcnt lgkmcnt(5)
	v_mfma_f32_32x32x16_bf16 v[66:81], v[214:217], v[114:117], v[66:81]
	s_waitcnt lgkmcnt(4)
	v_mfma_f32_32x32x16_bf16 v[66:81], v[224:227], v[118:121], v[66:81]
	s_waitcnt lgkmcnt(3)
	v_mfma_f32_32x32x16_bf16 v[66:81], v[232:235], v[122:125], v[66:81]
	s_waitcnt lgkmcnt(2)
	v_mfma_f32_32x32x16_bf16 v[66:81], v[236:239], v[126:129], v[66:81]
	s_waitcnt lgkmcnt(1)
	v_mfma_f32_32x32x16_bf16 v[66:81], v[240:243], v[130:133], v[66:81]
	s_waitcnt lgkmcnt(0)
	v_mfma_f32_32x32x16_bf16 v[66:81], v[184:187], v[134:137], v[66:81]
	s_and_saveexec_b64 s[14:15], s[0:1]
	s_cbranch_execz .Lpa1_nobias
	v_add_u32_e32 v190, v190, v148
	v_med3_i32 v188, v190, s39, 63
	v_lshl_add_u32 v188, v188, 2, s66
	v_add_u32_e32 v192, 1, v190
	v_med3_i32 v192, v192, s39, 63
	v_lshl_add_u32 v192, v192, 2, s66
	v_add_u32_e32 v193, 2, v190
	v_med3_i32 v193, v193, s39, 63
	v_lshl_add_u32 v193, v193, 2, s66
	v_add_u32_e32 v194, 3, v190
	v_med3_i32 v194, v194, s39, 63
	v_lshl_add_u32 v194, v194, 2, s66
	v_add_u32_e32 v195, 8, v190
	v_med3_i32 v195, v195, s39, 63
	v_lshl_add_u32 v195, v195, 2, s66
	v_add_u32_e32 v196, 9, v190
	v_med3_i32 v196, v196, s39, 63
	v_lshl_add_u32 v196, v196, 2, s66
	v_add_u32_e32 v199, 10, v190
	v_med3_i32 v199, v199, s39, 63
	v_lshl_add_u32 v199, v199, 2, s66
	v_add_u32_e32 v200, 11, v190
	v_med3_i32 v200, v200, s39, 63
	v_lshl_add_u32 v200, v200, 2, s66
	v_add_u32_e32 v202, 16, v190
	v_med3_i32 v202, v202, s39, 63
	v_lshl_add_u32 v202, v202, 2, s66
	v_add_u32_e32 v204, 17, v190
	v_med3_i32 v204, v204, s39, 63
	v_lshl_add_u32 v204, v204, 2, s66
	v_add_u32_e32 v205, 18, v190
	v_med3_i32 v205, v205, s39, 63
	v_lshl_add_u32 v205, v205, 2, s66
	v_add_u32_e32 v218, 19, v190
	v_med3_i32 v218, v218, s39, 63
	v_lshl_add_u32 v218, v218, 2, s66
	v_add_u32_e32 v219, 24, v190
	v_med3_i32 v219, v219, s39, 63
	v_lshl_add_u32 v219, v219, 2, s66
	v_add_u32_e32 v223, 25, v190
	v_med3_i32 v223, v223, s39, 63
	v_lshl_add_u32 v223, v223, 2, s66
	v_add_u32_e32 v244, 26, v190
	v_med3_i32 v244, v244, s39, 63
	v_lshl_add_u32 v244, v244, 2, s66
	v_add_u32_e32 v190, 27, v190
	v_med3_i32 v190, v190, s39, 63
	v_lshl_add_u32 v190, v190, 2, s66
	ds_read_b32 v188, v188 offset:512
	ds_read_b32 v192, v192 offset:512
	ds_read_b32 v193, v193 offset:512
	ds_read_b32 v194, v194 offset:512
	ds_read_b32 v195, v195 offset:512
	ds_read_b32 v196, v196 offset:512
	ds_read_b32 v199, v199 offset:512
	ds_read_b32 v200, v200 offset:512
	ds_read_b32 v202, v202 offset:512
	ds_read_b32 v204, v204 offset:512
	ds_read_b32 v205, v205 offset:512
	ds_read_b32 v218, v218 offset:512
	ds_read_b32 v219, v219 offset:512
	ds_read_b32 v223, v223 offset:512
	ds_read_b32 v244, v244 offset:512
	ds_read_b32 v190, v190 offset:512
	s_mov_b64 exec, s[14:15]
	ds_read2_b64 v[206:209], v198 offset1:2
	ds_read2_b64 v[210:213], v201 offset1:2
	ds_read2_b64 v[214:217], v203 offset1:2
	ds_read2_b64 v[224:227], v197 offset1:2
	ds_read2_b64 v[232:235], v198 offset0:4 offset1:6
	ds_read2_b64 v[236:239], v201 offset0:4 offset1:6
	ds_read2_b64 v[240:243], v203 offset0:4 offset1:6
	ds_read2_b64 v[184:187], v197 offset0:4 offset1:6
	s_waitcnt lgkmcnt(8)
	s_and_b64 exec, s[14:15], s[0:1]
	v_add_f32_e32 v66, v66, v188
	v_add_f32_e32 v67, v67, v192
	v_add_f32_e32 v68, v68, v193
	v_add_f32_e32 v69, v69, v194
	v_add_f32_e32 v70, v70, v195
	v_add_f32_e32 v71, v71, v196
	v_add_f32_e32 v72, v72, v199
	v_add_f32_e32 v73, v73, v200
	v_add_f32_e32 v74, v74, v202
	v_add_f32_e32 v75, v75, v204
	v_add_f32_e32 v76, v76, v205
	v_add_f32_e32 v77, v77, v218
	v_add_f32_e32 v78, v78, v219
	v_add_f32_e32 v79, v79, v223
	v_add_f32_e32 v80, v80, v244
	v_add_f32_e32 v81, v81, v190
	s_mov_b64 exec, s[14:15]
	s_branch .Lpa1_max
